# P0 Toeplitz item: log_dt/lam_re/lam_im parameter loads issued together with the b/c tile loads (were issued after those were waited for and written to LDS); on top of v134
# speedup vs baseline: 1.0037x; 1.0037x over previous
.LBB0_245:
	s_ashr_i32 s12, s48, 3
	s_lshl_b32 s0, s12, 10
	s_ashr_i32 s1, s0, 31
	s_lshl_b64 s[0:1], s[0:1], 2
	v_lshl_add_u64 v[0:1], v[14:15], 0, s[0:1]
	v_lshl_add_u64 v[4:5], v[16:17], 0, s[0:1]
	global_load_dwordx4 v[0:3], v[0:1], off
	s_nop 0
	global_load_dwordx4 v[4:7], v[4:5], off
	s_ashr_i32 s13, s12, 31
	v_readlane_b32 s66, v254, 17
	v_readlane_b32 s67, v254, 18
	v_readlane_b32 s64, v254, 15
	v_readlane_b32 s65, v254, 16
	v_readlane_b32 s62, v254, 13
	v_readlane_b32 s63, v254, 14
	s_lshl_b64 s[0:1], s[12:13], 2
	v_lshl_or_b32 v144, s12, 6, v221
	v_ashrrev_i32_e32 v145, 31, v144
	s_add_u32 s0, s66, s0
	s_addc_u32 s1, s67, s1
	v_lshlrev_b64 v[144:145], 2, v[144:145]
	global_load_dword v140, v13, s[0:1]
	v_lshl_add_u64 v[146:147], s[64:65], 0, v[144:145]
	global_load_dword v141, v[146:147], off
	v_lshl_add_u64 v[146:147], s[62:63], 0, v[144:145]
	global_load_dword v142, v[146:147], off
	s_and_b32 s49, s48, 7
	s_waitcnt vmcnt(4)
	ds_write_b128 v22, v[0:3]
	s_waitcnt vmcnt(3)
	ds_write_b128 v22, v[4:7] offset:8192
	s_and_saveexec_b64 s[14:15], s[4:5]
	s_cbranch_execz .LBB0_255
	s_ashr_i32 s13, s12, 31
	v_readlane_b32 s52, v254, 3
	s_lshl_b64 s[0:1], s[12:13], 2
	v_readlane_b32 s66, v254, 17
	v_readlane_b32 s67, v254, 18
	s_add_u32 s0, s66, s0
	s_addc_u32 s1, s67, s1
	v_lshl_or_b32 v0, s12, 6, v221
	v_ashrrev_i32_e32 v1, 31, v0
	v_readlane_b32 s64, v254, 15
	v_readlane_b32 s65, v254, 16
	v_lshlrev_b64 v[2:3], 2, v[0:1]
	v_readlane_b32 s62, v254, 13
	v_lshl_add_u64 v[0:1], s[64:65], 0, v[2:3]
	v_readlane_b32 s63, v254, 14
	v_readlane_b32 s53, v254, 4
	v_readlane_b32 s54, v254, 5
	v_lshl_add_u64 v[2:3], s[62:63], 0, v[2:3]
	v_readlane_b32 s55, v254, 6
	v_readlane_b32 s56, v254, 7
	v_readlane_b32 s57, v254, 8
	v_readlane_b32 s58, v254, 9
	v_readlane_b32 s59, v254, 10
	v_readlane_b32 s60, v254, 11
	v_readlane_b32 s61, v254, 12
	s_waitcnt vmcnt(2)
	v_mov_b32_e32 v6, v140
	v_mul_f32_e32 v1, 0x3fb8aa3b, v6
	v_fma_f32 v2, v6, s20, -v1
	v_rndne_f32_e32 v3, v1
	v_fmac_f32_e32 v2, 0x32a5705f, v6
	v_sub_f32_e32 v1, v1, v3
	v_add_f32_e32 v1, v1, v2
	v_cvt_i32_f32_e32 v3, v3
	v_exp_f32_e32 v1, v1
	v_cmp_ngt_f32_e32 vcc, s21, v6
	v_lshl_or_b32 v2, s49, 2, v101
	v_cvt_f32_ubyte0_e32 v5, v2
	v_ldexp_f32 v1, v1, v3
	v_cndmask_b32_e32 v1, 0, v1, vcc
	v_cmp_nlt_f32_e32 vcc, s22, v6
	s_nop 1
	v_cndmask_b32_e32 v6, v38, v1, vcc
	s_waitcnt vmcnt(1)
	v_mov_b32_e32 v0, v141
	v_mul_f32_e32 v1, v0, v6
	v_mul_f32_e32 v2, v1, v5
	v_and_b32_e32 v3, 0x7fffffff, v2
	v_cmp_nlt_f32_e64 s[0:1], |v2|, s23
	s_and_saveexec_b64 s[6:7], s[0:1]
	s_xor_b64 s[18:19], exec, s[6:7]
	s_cbranch_execz .LBB0_248
	v_lshrrev_b32_e32 v7, 23, v3
	v_add_u32_e32 v7, 0xffffff88, v7
	v_cmp_lt_u32_e32 vcc, 63, v7
	s_nop 1
	v_cndmask_b32_e32 v8, 0, v39, vcc
	v_add_u32_e32 v7, v8, v7
	v_cmp_lt_u32_e64 s[0:1], 31, v7
	s_nop 1
	v_cndmask_b32_e64 v8, 0, v40, s[0:1]
	v_add_u32_e32 v7, v8, v7
	v_cmp_lt_u32_e64 s[6:7], 31, v7
	s_nop 1
	v_cndmask_b32_e64 v8, 0, v40, s[6:7]
	v_add_u32_e32 v7, v8, v7
	v_and_b32_e32 v8, 0x7fffff, v3
	v_or_b32_e32 v19, 0x800000, v8
	v_mad_u64_u32 v[8:9], s[8:9], v19, s33, 0
	v_mov_b32_e32 v12, v9
	v_mad_u64_u32 v[10:11], s[8:9], v19, s34, v[12:13]
	v_mov_b32_e32 v12, v11
	v_mad_u64_u32 v[20:21], s[8:9], v19, s35, v[12:13]
	v_mov_b32_e32 v12, v21
	v_mad_u64_u32 v[42:43], s[8:9], v19, s36, v[12:13]
	v_mov_b32_e32 v12, v43
	v_mad_u64_u32 v[44:45], s[8:9], v19, s37, v[12:13]
	v_mov_b32_e32 v12, v45
	v_mad_u64_u32 v[46:47], s[8:9], v19, s38, v[12:13]
	v_mov_b32_e32 v12, v47
	v_mad_u64_u32 v[48:49], s[8:9], v19, s39, v[12:13]
	v_cndmask_b32_e32 v9, v46, v42, vcc
	v_cndmask_b32_e32 v11, v48, v44, vcc
	v_cndmask_b32_e32 v19, v49, v46, vcc
	v_cndmask_b32_e64 v12, v11, v9, s[0:1]
	v_cndmask_b32_e64 v11, v19, v11, s[0:1]
	v_cndmask_b32_e32 v19, v44, v20, vcc
	v_cndmask_b32_e64 v9, v9, v19, s[0:1]
	v_sub_u32_e32 v21, 32, v7
	v_cmp_eq_u32_e64 s[8:9], 0, v7
	v_cndmask_b32_e32 v7, v42, v10, vcc
	v_cndmask_b32_e64 v11, v11, v12, s[6:7]
	v_cndmask_b32_e64 v12, v12, v9, s[6:7]
	v_cndmask_b32_e64 v10, v19, v7, s[0:1]
	v_alignbit_b32 v43, v11, v12, v21
	v_cndmask_b32_e64 v9, v9, v10, s[6:7]
	v_cndmask_b32_e64 v11, v43, v11, s[8:9]
	v_alignbit_b32 v19, v12, v9, v21
	v_cndmask_b32_e32 v8, v20, v8, vcc
	v_cndmask_b32_e64 v12, v19, v12, s[8:9]
	v_bfe_u32 v43, v11, 29, 1
	v_cndmask_b32_e64 v7, v7, v8, s[0:1]
	v_alignbit_b32 v19, v11, v12, 30
	v_sub_u32_e32 v44, 0, v43
	v_cndmask_b32_e64 v7, v10, v7, s[6:7]
	v_xor_b32_e32 v19, v19, v44
	v_alignbit_b32 v8, v9, v7, v21
	v_cndmask_b32_e64 v8, v8, v9, s[8:9]
	v_ffbh_u32_e32 v10, v19
	v_alignbit_b32 v9, v12, v8, 30
	v_min_u32_e32 v10, 32, v10
	v_alignbit_b32 v7, v8, v7, 30
	v_xor_b32_e32 v9, v9, v44
	v_sub_u32_e32 v12, 31, v10
	v_xor_b32_e32 v7, v7, v44
	v_alignbit_b32 v19, v19, v9, v12
	v_alignbit_b32 v7, v9, v7, v12
	v_alignbit_b32 v8, v19, v7, 9
	v_ffbh_u32_e32 v9, v8
	v_min_u32_e32 v9, 32, v9
	v_lshrrev_b32_e32 v42, 29, v11
	v_not_b32_e32 v12, v9
	v_alignbit_b32 v7, v8, v7, v12
	v_lshlrev_b32_e32 v8, 31, v42
	v_or_b32_e32 v12, 0x33000000, v8
	v_add_lshl_u32 v9, v9, v10, 23
	v_lshrrev_b32_e32 v7, 9, v7
	v_sub_u32_e32 v9, v12, v9
	v_or_b32_e32 v8, 0.5, v8
	v_lshlrev_b32_e32 v10, 23, v10
	v_or_b32_e32 v7, v9, v7
	v_lshrrev_b32_e32 v9, 9, v19
	v_sub_u32_e32 v8, v8, v10
	v_or_b32_e32 v8, v9, v8
	v_mul_f32_e32 v9, 0x3fc90fda, v8
	v_fma_f32 v10, v8, s40, -v9
	v_fmac_f32_e32 v10, 0x33a22168, v8
	v_fmac_f32_e32 v10, 0x3fc90fda, v7
	v_lshrrev_b32_e32 v8, 30, v11
	v_add_f32_e32 v7, v9, v10
	v_add_u32_e32 v9, v43, v8

.LBB0_252:
	s_andn2_saveexec_b64 s[0:1], s[18:19]
	v_mul_f32_e64 v10, |v1|, s41
	v_rndne_f32_e32 v12, v10
	v_cvt_i32_f32_e32 v11, v12
	v_fma_f32 v10, v12, s42, |v1|
	v_fmac_f32_e32 v10, 0xb3a22168, v12
	v_fmac_f32_e32 v10, 0xa7c234c4, v12
	s_or_b64 exec, exec, s[0:1]
	s_waitcnt vmcnt(0)
	v_mov_b32_e32 v4, v142
	v_max_f32_e32 v4, v4, v4
	v_min_f32_e32 v4, 0xb8d1b717, v4
	v_mul_f32_e32 v6, v4, v6
	v_mul_f32_e32 v5, v6, v5
	v_mul_f32_e32 v12, 0x3fb8aa3b, v5
	v_fma_f32 v19, v5, s20, -v12
	v_rndne_f32_e32 v20, v12
	v_fmac_f32_e32 v19, 0x32a5705f, v5
	v_sub_f32_e32 v12, v12, v20
	v_add_f32_e32 v12, v12, v19
	v_cvt_i32_f32_e32 v19, v20
	v_exp_f32_e32 v12, v12
	v_cmp_ngt_f32_e32 vcc, s21, v5
	v_xor_b32_e32 v3, v3, v2
	v_cmp_ngt_f32_e64 s[0:1], s21, v6
	v_ldexp_f32 v12, v12, v19
	v_cndmask_b32_e32 v12, 0, v12, vcc
	v_cmp_nlt_f32_e32 vcc, s22, v5
	v_xor_b32_e32 v8, v8, v1
	s_nop 0
	v_cndmask_b32_e32 v5, v38, v12, vcc
	v_mul_f32_e32 v12, v7, v7
	v_fmamk_f32 v19, v12, 0xb94c1982, v35
	v_fmaak_f32 v19, v12, v19, 0xbe2aaa9d
	v_mul_f32_e32 v19, v12, v19
	v_fmac_f32_e32 v7, v7, v19
	v_fmamk_f32 v19, v12, 0x37d75334, v36
	v_fmaak_f32 v19, v12, v19, 0x3d2aabf7
	v_fmaak_f32 v19, v12, v19, 0xbf000004
	v_fma_f32 v12, v12, v19, 1.0
	v_lshlrev_b32_e32 v19, 30, v9
	v_and_b32_e32 v9, 1, v9
	v_cmp_eq_u32_e32 vcc, 0, v9
	v_and_b32_e32 v20, 0x80000000, v19
	s_nop 0
	v_cndmask_b32_e32 v9, v12, v7, vcc
	v_xor_b32_e32 v3, v3, v9
	v_xor_b32_e32 v7, 0x80000000, v7
	v_mul_f32_e32 v9, 0x3fb8aa3b, v6
	v_xor_b32_e32 v3, v3, v20
	v_cndmask_b32_e32 v7, v7, v12, vcc
	v_fma_f32 v12, v6, s20, -v9
	v_rndne_f32_e32 v20, v9
	v_fmac_f32_e32 v12, 0x32a5705f, v6
	v_sub_f32_e32 v9, v9, v20
	v_add_f32_e32 v9, v9, v12
	v_exp_f32_e32 v9, v9
	v_cvt_i32_f32_e32 v12, v20
	v_bitop3_b32 v7, v7, v19, s43 bitop3:0x78
	v_cmp_class_f32_e64 vcc, v2, s44
	s_nop 1
	v_cndmask_b32_e32 v2, v41, v7, vcc
	v_ldexp_f32 v7, v9, v12
	v_cndmask_b32_e64 v7, 0, v7, s[0:1]
	v_cmp_nlt_f32_e64 s[0:1], s22, v6
	v_cndmask_b32_e32 v3, v41, v3, vcc
	v_mul_f32_e32 v2, v5, v2
	v_cndmask_b32_e64 v6, v38, v7, s[0:1]
	v_mul_f32_e32 v7, v10, v10
	v_fmamk_f32 v9, v7, 0xb94c1982, v35
	v_fmaak_f32 v9, v7, v9, 0xbe2aaa9d
	v_mul_f32_e32 v9, v7, v9
	v_fmac_f32_e32 v10, v10, v9
	v_fmamk_f32 v9, v7, 0x37d75334, v36
	v_fmaak_f32 v9, v7, v9, 0x3d2aabf7
	v_fmaak_f32 v9, v7, v9, 0xbf000004
	v_fma_f32 v7, v7, v9, 1.0
	v_lshlrev_b32_e32 v9, 30, v11
	v_and_b32_e32 v11, 1, v11
	v_cmp_eq_u32_e64 s[0:1], 0, v11
	v_and_b32_e32 v12, 0x80000000, v9
	v_mul_f32_e32 v3, v5, v3
	v_cndmask_b32_e64 v11, v7, v10, s[0:1]
	v_xor_b32_e32 v10, 0x80000000, v10
	v_xor_b32_e32 v8, v8, v11
	v_cndmask_b32_e64 v7, v10, v7, s[0:1]
	v_xor_b32_e32 v8, v8, v12
	v_bitop3_b32 v7, v7, v9, s43 bitop3:0x78
	v_cmp_class_f32_e64 s[0:1], v1, s44
	s_nop 1
	v_cndmask_b32_e64 v1, v41, v7, s[0:1]
	v_cndmask_b32_e64 v7, v41, v8, s[0:1]
	v_mul_f32_e32 v7, v6, v7
	v_fma_f32 v1, v6, v1, -1.0
	v_mul_f32_e32 v6, v0, v0
	v_mul_f32_e32 v8, v0, v7
	v_fmac_f32_e32 v6, v4, v4
	v_fmac_f32_e32 v8, v4, v1
	v_div_scale_f32 v9, s[0:1], v6, v6, v8
	v_rcp_f32_e32 v10, v9
	v_mul_f32_e32 v0, v0, v1
	v_fma_f32 v0, v4, v7, -v0
	v_div_scale_f32 v1, s[0:1], v6, v6, v0
	v_fma_f32 v5, -v9, v10, 1.0
	v_fmac_f32_e32 v10, v5, v10
	v_div_scale_f32 v5, vcc, v8, v6, v8
	v_rcp_f32_e32 v4, v1
	v_mul_f32_e32 v11, v5, v10
	v_fma_f32 v12, -v9, v11, v5
	v_fmac_f32_e32 v11, v12, v10
	v_fma_f32 v5, -v9, v11, v5
	v_fma_f32 v7, -v1, v4, 1.0
	v_div_fmas_f32 v5, v5, v10, v11
	v_fmac_f32_e32 v4, v7, v4
	v_div_scale_f32 v7, vcc, v0, v6, v0
	v_div_fixup_f32 v5, v5, v6, v8
	v_mul_f32_e32 v8, v7, v4
	v_fma_f32 v9, -v1, v8, v7
	v_fmac_f32_e32 v8, v9, v4
	v_fma_f32 v1, -v1, v8, v7
	v_div_fmas_f32 v1, v1, v4, v8
	v_div_fixup_f32 v0, v1, v6, v0
	v_mul_f32_e32 v1, v3, v0
	v_mul_f32_e32 v3, v3, v5
	v_fma_f32 v1, v2, v5, -v1
	v_fmac_f32_e32 v3, v2, v0
	ds_write2st64_b32 v37, v1, v3 offset0:64 offset1:68
